# scan loop: global instead of flat for prefetch loads/O stores, vmcnt wait moved before stores; ctx_fourier: 32 loads hoisted per 16-t block with counted vmcnt
# baseline (speedup 1.0000x reference)
.LBB0_1354:
	s_lshl_b32 s30, s40, 9
	v_lshl_add_u64 v[36:37], s[30:31], 2, v[6:7]
	v_mov_b32_e32 v38, 0x1000
	v_mov_b32_e32 v39, 0
	global_load_dword v40, v[36:37], off
	global_load_dword v41, v[36:37], off offset:1024
	global_load_dword v42, v[36:37], off offset:2048
	global_load_dword v43, v[36:37], off offset:3072
	v_lshl_add_u64 v[36:37], v[36:37], 0, v[38:39]
	global_load_dword v44, v[36:37], off
	global_load_dword v45, v[36:37], off offset:1024
	global_load_dword v46, v[36:37], off offset:2048
	global_load_dword v47, v[36:37], off offset:3072
	v_lshl_add_u64 v[36:37], v[36:37], 0, v[38:39]
	global_load_dword v48, v[36:37], off
	global_load_dword v49, v[36:37], off offset:1024
	global_load_dword v50, v[36:37], off offset:2048
	global_load_dword v51, v[36:37], off offset:3072
	v_lshl_add_u64 v[36:37], v[36:37], 0, v[38:39]
	global_load_dword v52, v[36:37], off
	global_load_dword v53, v[36:37], off offset:1024
	global_load_dword v54, v[36:37], off offset:2048
	global_load_dword v55, v[36:37], off offset:3072
	v_lshl_add_u64 v[36:37], v[36:37], 0, v[38:39]
	global_load_dword v56, v[36:37], off
	global_load_dword v57, v[36:37], off offset:1024
	global_load_dword v58, v[36:37], off offset:2048
	global_load_dword v59, v[36:37], off offset:3072
	v_lshl_add_u64 v[36:37], v[36:37], 0, v[38:39]
	global_load_dword v60, v[36:37], off
	global_load_dword v61, v[36:37], off offset:1024
	global_load_dword v62, v[36:37], off offset:2048
	global_load_dword v63, v[36:37], off offset:3072
	v_lshl_add_u64 v[36:37], v[36:37], 0, v[38:39]
	global_load_dword v64, v[36:37], off
	global_load_dword v65, v[36:37], off offset:1024
	global_load_dword v66, v[36:37], off offset:2048
	global_load_dword v67, v[36:37], off offset:3072
	v_lshl_add_u64 v[36:37], v[36:37], 0, v[38:39]
	global_load_dword v68, v[36:37], off
	global_load_dword v69, v[36:37], off offset:1024
	global_load_dword v70, v[36:37], off offset:2048
	global_load_dword v71, v[36:37], off offset:3072
	s_lshl_b32 s30, s40, 9
	v_lshl_add_u64 v[16:17], s[30:31], 2, v[6:7]
	s_lshl_b32 s30, s40, 2
	v_mul_lo_u32 v19, s30, v21
	v_and_b32_e32 v16, 0x200, v19
	v_add_u32_e32 v19, s30, v19
	v_and_b32_e32 v23, 0x3c0, v19
	v_add_u32_e32 v16, 0, v16
	v_add_u32_e32 v23, 0, v23
	ds_read2st64_b32 v[16:17], v16 offset1:4
	ds_read2st64_b32 v[26:27], v23 offset1:4
	s_or_b32 s41, s40, 1
	s_waitcnt lgkmcnt(0)
	v_mov_b32_e32 v28, v16
	v_mov_b32_e32 v29, v26
	v_mov_b32_e32 v26, v17
	s_waitcnt vmcnt(30)
	v_mov_b32_e32 v18, v40
	v_mov_b32_e32 v24, v41
	v_pk_mul_f32 v[16:17], v[24:25], v[26:27] op_sel_hi:[0,1]
	v_pk_fma_f32 v[16:17], v[18:19], v[28:29], v[16:17] op_sel_hi:[0,1,1] neg_lo:[0,0,1] neg_hi:[0,0,1]
	v_add_u32_e32 v19, s30, v19
	v_pk_add_f32 v[14:15], v[14:15], v[16:17]
	v_and_b32_e32 v16, 0x380, v19
	v_add_u32_e32 v19, s30, v19
	v_and_b32_e32 v23, 0x3c0, v19
	v_add_u32_e32 v16, 0, v16
	v_add_u32_e32 v23, 0, v23
	ds_read2st64_b32 v[16:17], v16 offset1:4
	ds_read2st64_b32 v[26:27], v23 offset1:4
	s_waitcnt lgkmcnt(1)
	v_mov_b32_e32 v28, v16
	s_waitcnt lgkmcnt(0)
	v_mov_b32_e32 v29, v26
	v_mov_b32_e32 v26, v17
	v_pk_mul_f32 v[16:17], v[24:25], v[26:27] op_sel_hi:[0,1]
	v_pk_fma_f32 v[16:17], v[18:19], v[28:29], v[16:17] op_sel_hi:[0,1,1] neg_lo:[0,0,1] neg_hi:[0,0,1]
	v_add_u32_e32 v19, s30, v19
	v_pk_add_f32 v[12:13], v[12:13], v[16:17]
	v_and_b32_e32 v16, 0x300, v19
	v_add_u32_e32 v19, s30, v19
	v_and_b32_e32 v23, 0x3c0, v19
	v_add_u32_e32 v16, 0, v16
	v_add_u32_e32 v23, 0, v23
	ds_read2st64_b32 v[16:17], v16 offset1:4
	ds_read2st64_b32 v[26:27], v23 offset1:4
	s_waitcnt lgkmcnt(1)
	v_mov_b32_e32 v28, v16
	s_waitcnt lgkmcnt(0)
	v_mov_b32_e32 v29, v26
	v_mov_b32_e32 v26, v17
	v_pk_mul_f32 v[16:17], v[24:25], v[26:27] op_sel_hi:[0,1]
	v_pk_fma_f32 v[16:17], v[18:19], v[28:29], v[16:17] op_sel_hi:[0,1,1] neg_lo:[0,0,1] neg_hi:[0,0,1]
	v_pk_add_f32 v[16:17], v[10:11], v[16:17]
	v_add_u32_e32 v10, s30, v19
	v_and_b32_e32 v10, 0x380, v10
	v_add_u32_e32 v10, 0, v10
	ds_read2st64_b32 v[10:11], v10 offset1:4
	v_mov_b32_e32 v19, v24
	s_waitcnt lgkmcnt(0)
	v_mul_f32_e32 v26, v24, v11
	v_mul_lo_u32 v11, s30, v22
	v_and_b32_e32 v11, 0x3c0, v11
	v_add_u32_e32 v11, 0, v11
	ds_read2st64_b32 v[28:29], v11 offset1:4
	v_mul_f32_e32 v10, v18, v10
	s_lshl_b32 s30, s41, 9
	s_waitcnt lgkmcnt(0)
	v_pk_mul_f32 v[18:19], v[18:19], v[28:29]
	s_nop 0
	v_mov_b32_e32 v11, v18
	v_mov_b32_e32 v27, v19
	v_pk_add_f32 v[10:11], v[10:11], v[26:27] neg_lo:[0,1] neg_hi:[0,1]
	s_nop 0
	v_pk_add_f32 v[18:19], v[8:9], v[10:11]
	v_lshl_add_u64 v[8:9], s[30:31], 2, v[6:7]
	s_lshl_b32 s30, s41, 2
	v_mul_lo_u32 v10, s30, v21
	v_add_u32_e32 v23, s30, v10
	v_and_b32_e32 v8, 0x3e0, v10
	v_and_b32_e32 v10, 0x3e4, v23
	v_add_u32_e32 v8, 0, v8
	v_add_u32_e32 v10, 0, v10
	ds_read2st64_b32 v[8:9], v8 offset1:4
	ds_read2st64_b32 v[10:11], v10 offset1:4
	s_or_b32 s41, s40, 2
	s_waitcnt lgkmcnt(0)
	v_mov_b32_e32 v28, v8
	v_mov_b32_e32 v29, v10
	v_mov_b32_e32 v10, v9
	s_waitcnt vmcnt(28)
	v_mov_b32_e32 v24, v42
	v_mov_b32_e32 v26, v43
	v_pk_mul_f32 v[8:9], v[26:27], v[10:11] op_sel_hi:[0,1]
	v_pk_fma_f32 v[8:9], v[24:25], v[28:29], v[8:9] op_sel_hi:[0,1,1] neg_lo:[0,0,1] neg_hi:[0,0,1]
	v_pk_add_f32 v[8:9], v[14:15], v[8:9]
	v_add_u32_e32 v14, s30, v23
	v_add_u32_e32 v23, s30, v14
	v_and_b32_e32 v10, 0x3e8, v14
	v_and_b32_e32 v14, 0x3ec, v23
	v_add_u32_e32 v10, 0, v10
	v_add_u32_e32 v14, 0, v14
	ds_read2st64_b32 v[10:11], v10 offset1:4
	ds_read2st64_b32 v[14:15], v14 offset1:4
	s_waitcnt lgkmcnt(1)
	v_mov_b32_e32 v28, v10
	s_waitcnt lgkmcnt(0)
	v_mov_b32_e32 v29, v14
	v_mov_b32_e32 v14, v11
	v_pk_mul_f32 v[10:11], v[26:27], v[14:15] op_sel_hi:[0,1]
	v_add_u32_e32 v14, s30, v23
	v_pk_fma_f32 v[10:11], v[24:25], v[28:29], v[10:11] op_sel_hi:[0,1,1] neg_lo:[0,0,1] neg_hi:[0,0,1]
	v_add_u32_e32 v23, s30, v14
	v_pk_add_f32 v[10:11], v[12:13], v[10:11]
	v_and_b32_e32 v12, 0x3f0, v14
	v_and_b32_e32 v14, 0x3f4, v23
	v_add_u32_e32 v12, 0, v12
	v_add_u32_e32 v14, 0, v14
	ds_read2st64_b32 v[12:13], v12 offset1:4
	ds_read2st64_b32 v[14:15], v14 offset1:4
	s_waitcnt lgkmcnt(1)
	v_mov_b32_e32 v28, v12
	s_waitcnt lgkmcnt(0)
	v_mov_b32_e32 v29, v14
	v_mov_b32_e32 v14, v13
	v_pk_mul_f32 v[12:13], v[26:27], v[14:15] op_sel_hi:[0,1]
	v_add_u32_e32 v14, s30, v23
	v_and_b32_e32 v14, 0x3f8, v14
	v_add_u32_e32 v14, 0, v14
	ds_read2st64_b32 v[14:15], v14 offset1:4
	v_pk_fma_f32 v[12:13], v[24:25], v[28:29], v[12:13] op_sel_hi:[0,1,1] neg_lo:[0,0,1] neg_hi:[0,0,1]
	v_pk_add_f32 v[12:13], v[16:17], v[12:13]
	v_mov_b32_e32 v25, v26
	s_waitcnt lgkmcnt(0)
	v_mul_f32_e32 v16, v26, v15
	v_mul_lo_u32 v15, s30, v22
	v_and_b32_e32 v15, 0x3fc, v15
	v_add_u32_e32 v15, 0, v15
	ds_read2st64_b32 v[28:29], v15 offset1:4
	v_mul_f32_e32 v14, v24, v14
	s_lshl_b32 s30, s41, 9
	s_waitcnt lgkmcnt(0)
	v_pk_mul_f32 v[24:25], v[24:25], v[28:29]
	s_nop 0
	v_mov_b32_e32 v15, v24
	v_mov_b32_e32 v17, v25
	v_pk_add_f32 v[14:15], v[14:15], v[16:17] neg_lo:[0,1] neg_hi:[0,1]
	v_lshl_add_u64 v[16:17], s[30:31], 2, v[6:7]
	v_pk_add_f32 v[14:15], v[18:19], v[14:15]
	s_nop 0
	s_lshl_b32 s30, s41, 2
	v_mul_lo_u32 v17, s30, v21
	v_and_b32_e32 v19, 0x3c0, v17
	v_add_u32_e32 v19, 0, v19
	v_add_u32_e32 v17, s30, v17
	ds_read2st64_b32 v[24:25], v19 offset1:4
	v_and_b32_e32 v19, 0x3c8, v17
	v_add_u32_e32 v19, 0, v19
	ds_read2st64_b32 v[26:27], v19 offset1:4
	s_or_b32 s41, s40, 3
	s_waitcnt lgkmcnt(0)
	v_mov_b32_e32 v28, v24
	v_mov_b32_e32 v29, v26
	v_mov_b32_e32 v26, v25
	s_waitcnt vmcnt(26)
	v_mov_b32_e32 v18, v44
	v_mov_b32_e32 v16, v45
	v_pk_mul_f32 v[24:25], v[16:17], v[26:27] op_sel_hi:[0,1]
	v_add_u32_e32 v17, s30, v17
	v_pk_fma_f32 v[24:25], v[18:19], v[28:29], v[24:25] op_sel_hi:[0,1,1] neg_lo:[0,0,1] neg_hi:[0,0,1]
	v_and_b32_e32 v19, 0x3d0, v17
	v_add_u32_e32 v19, 0, v19
	v_add_u32_e32 v17, s30, v17
	v_pk_add_f32 v[8:9], v[8:9], v[24:25]
	ds_read2st64_b32 v[24:25], v19 offset1:4
	v_and_b32_e32 v19, 0x3d8, v17
	v_add_u32_e32 v19, 0, v19
	ds_read2st64_b32 v[26:27], v19 offset1:4
	s_waitcnt lgkmcnt(1)
	v_mov_b32_e32 v28, v24
	s_waitcnt lgkmcnt(0)
	v_mov_b32_e32 v29, v26
	v_mov_b32_e32 v26, v25
	v_pk_mul_f32 v[24:25], v[16:17], v[26:27] op_sel_hi:[0,1]
	v_add_u32_e32 v17, s30, v17
	v_pk_fma_f32 v[24:25], v[18:19], v[28:29], v[24:25] op_sel_hi:[0,1,1] neg_lo:[0,0,1] neg_hi:[0,0,1]
	v_and_b32_e32 v19, 0x3e0, v17
	v_add_u32_e32 v19, 0, v19
	v_add_u32_e32 v17, s30, v17
	v_pk_add_f32 v[10:11], v[10:11], v[24:25]
	ds_read2st64_b32 v[24:25], v19 offset1:4
	v_and_b32_e32 v19, 0x3e8, v17
	v_add_u32_e32 v19, 0, v19
	ds_read2st64_b32 v[26:27], v19 offset1:4
	s_waitcnt lgkmcnt(1)
	v_mov_b32_e32 v28, v24
	s_waitcnt lgkmcnt(0)
	v_mov_b32_e32 v29, v26
	v_mov_b32_e32 v26, v25
	v_pk_mul_f32 v[24:25], v[16:17], v[26:27] op_sel_hi:[0,1]
	v_add_u32_e32 v17, s30, v17
	v_and_b32_e32 v17, 0x3f0, v17
	v_pk_fma_f32 v[24:25], v[18:19], v[28:29], v[24:25] op_sel_hi:[0,1,1] neg_lo:[0,0,1] neg_hi:[0,0,1]
	v_add_u32_e32 v17, 0, v17
	v_pk_add_f32 v[12:13], v[12:13], v[24:25]
	ds_read2st64_b32 v[24:25], v17 offset1:4
	v_mul_lo_u32 v17, s30, v22
	v_and_b32_e32 v17, 0x3f8, v17
	v_add_u32_e32 v17, 0, v17
	ds_read2st64_b32 v[28:29], v17 offset1:4
	v_mov_b32_e32 v19, v16
	s_waitcnt lgkmcnt(1)
	v_mul_f32_e32 v26, v16, v25
	v_mul_f32_e32 v24, v18, v24
	s_lshl_b32 s30, s41, 9
	s_waitcnt lgkmcnt(0)
	v_pk_mul_f32 v[16:17], v[18:19], v[28:29]
	s_nop 0
	v_mov_b32_e32 v25, v16
	v_mov_b32_e32 v27, v17
	v_pk_add_f32 v[16:17], v[24:25], v[26:27] neg_lo:[0,1] neg_hi:[0,1]
	s_nop 0
	v_pk_add_f32 v[14:15], v[14:15], v[16:17]
	v_lshl_add_u64 v[16:17], s[30:31], 2, v[6:7]
	s_nop 0
	s_lshl_b32 s30, s41, 2
	v_mul_lo_u32 v17, s30, v21
	v_and_b32_e32 v19, 0x3e0, v17
	v_add_u32_e32 v19, 0, v19
	v_add_u32_e32 v17, s30, v17
	ds_read2st64_b32 v[24:25], v19 offset1:4
	v_and_b32_e32 v19, 0x3ec, v17
	v_add_u32_e32 v19, 0, v19
	ds_read2st64_b32 v[26:27], v19 offset1:4
	s_or_b32 s41, s40, 4
	s_waitcnt lgkmcnt(0)
	v_mov_b32_e32 v28, v24
	v_mov_b32_e32 v29, v26
	v_mov_b32_e32 v26, v25
	s_waitcnt vmcnt(24)
	v_mov_b32_e32 v18, v46
	v_mov_b32_e32 v16, v47
	v_pk_mul_f32 v[24:25], v[16:17], v[26:27] op_sel_hi:[0,1]
	v_add_u32_e32 v17, s30, v17
	v_pk_fma_f32 v[24:25], v[18:19], v[28:29], v[24:25] op_sel_hi:[0,1,1] neg_lo:[0,0,1] neg_hi:[0,0,1]
	v_and_b32_e32 v19, 0x3f8, v17
	v_add_u32_e32 v19, 0, v19
	v_add_u32_e32 v17, s30, v17
	v_pk_add_f32 v[8:9], v[8:9], v[24:25]
	ds_read2st64_b32 v[24:25], v19 offset1:4
	v_and_b32_e32 v19, 0x3e4, v17
	v_add_u32_e32 v19, 0, v19
	ds_read2st64_b32 v[26:27], v19 offset1:4
	s_waitcnt lgkmcnt(1)
	v_mov_b32_e32 v28, v24
	s_waitcnt lgkmcnt(0)
	v_mov_b32_e32 v29, v26
	v_mov_b32_e32 v26, v25
	v_pk_mul_f32 v[24:25], v[16:17], v[26:27] op_sel_hi:[0,1]
	v_add_u32_e32 v17, s30, v17
	v_pk_fma_f32 v[24:25], v[18:19], v[28:29], v[24:25] op_sel_hi:[0,1,1] neg_lo:[0,0,1] neg_hi:[0,0,1]
	v_and_b32_e32 v19, 0x3f0, v17
	v_add_u32_e32 v19, 0, v19
	v_add_u32_e32 v17, s30, v17
	v_pk_add_f32 v[10:11], v[10:11], v[24:25]
	ds_read2st64_b32 v[24:25], v19 offset1:4
	v_and_b32_e32 v19, 0x3fc, v17
	v_add_u32_e32 v19, 0, v19
	ds_read2st64_b32 v[26:27], v19 offset1:4
	s_waitcnt lgkmcnt(1)
	v_mov_b32_e32 v28, v24
	s_waitcnt lgkmcnt(0)
	v_mov_b32_e32 v29, v26
	v_mov_b32_e32 v26, v25
	v_pk_mul_f32 v[24:25], v[16:17], v[26:27] op_sel_hi:[0,1]
	v_add_u32_e32 v17, s30, v17
	v_and_b32_e32 v17, 0x3e8, v17
	v_pk_fma_f32 v[24:25], v[18:19], v[28:29], v[24:25] op_sel_hi:[0,1,1] neg_lo:[0,0,1] neg_hi:[0,0,1]
	v_add_u32_e32 v17, 0, v17
	v_pk_add_f32 v[12:13], v[12:13], v[24:25]
	ds_read2st64_b32 v[24:25], v17 offset1:4
	v_mul_lo_u32 v17, s30, v22
	v_and_b32_e32 v17, 0x3f4, v17
	v_add_u32_e32 v17, 0, v17
	ds_read2st64_b32 v[28:29], v17 offset1:4
	v_mov_b32_e32 v19, v16
	s_waitcnt lgkmcnt(1)
	v_mul_f32_e32 v26, v16, v25
	v_mul_f32_e32 v24, v18, v24
	s_lshl_b32 s30, s41, 9
	s_waitcnt lgkmcnt(0)
	v_pk_mul_f32 v[16:17], v[18:19], v[28:29]
	s_nop 0
	v_mov_b32_e32 v25, v16
	v_mov_b32_e32 v27, v17
	v_pk_add_f32 v[16:17], v[24:25], v[26:27] neg_lo:[0,1] neg_hi:[0,1]
	s_nop 0
	v_pk_add_f32 v[14:15], v[14:15], v[16:17]
	v_lshl_add_u64 v[16:17], s[30:31], 2, v[6:7]
	s_nop 0
	s_lshl_b32 s30, s41, 2
	v_mul_lo_u32 v17, s30, v21
	v_and_b32_e32 v19, 0x380, v17
	v_add_u32_e32 v19, 0, v19
	v_add_u32_e32 v17, s30, v17
	ds_read2st64_b32 v[24:25], v19 offset1:4
	v_and_b32_e32 v19, 0x3d0, v17
	v_add_u32_e32 v19, 0, v19
	ds_read2st64_b32 v[26:27], v19 offset1:4
	s_or_b32 s41, s40, 5
	s_waitcnt lgkmcnt(0)
	v_mov_b32_e32 v28, v24
	v_mov_b32_e32 v29, v26
	v_mov_b32_e32 v26, v25
	s_waitcnt vmcnt(22)
	v_mov_b32_e32 v18, v48
	v_mov_b32_e32 v16, v49
	v_pk_mul_f32 v[24:25], v[16:17], v[26:27] op_sel_hi:[0,1]
	v_add_u32_e32 v17, s30, v17
	v_pk_fma_f32 v[24:25], v[18:19], v[28:29], v[24:25] op_sel_hi:[0,1,1] neg_lo:[0,0,1] neg_hi:[0,0,1]
	v_and_b32_e32 v19, 0x3a0, v17
	v_add_u32_e32 v19, 0, v19
	v_add_u32_e32 v17, s30, v17
	v_pk_add_f32 v[8:9], v[8:9], v[24:25]
	ds_read2st64_b32 v[24:25], v19 offset1:4
	v_and_b32_e32 v19, 0x3f0, v17
	v_add_u32_e32 v19, 0, v19
	ds_read2st64_b32 v[26:27], v19 offset1:4
	s_waitcnt lgkmcnt(1)
	v_mov_b32_e32 v28, v24
	s_waitcnt lgkmcnt(0)
	v_mov_b32_e32 v29, v26
	v_mov_b32_e32 v26, v25
	v_pk_mul_f32 v[24:25], v[16:17], v[26:27] op_sel_hi:[0,1]
	v_add_u32_e32 v17, s30, v17
	v_pk_fma_f32 v[24:25], v[18:19], v[28:29], v[24:25] op_sel_hi:[0,1,1] neg_lo:[0,0,1] neg_hi:[0,0,1]
	v_and_b32_e32 v19, 0x3c0, v17
	v_add_u32_e32 v19, 0, v19
	v_add_u32_e32 v17, s30, v17
	v_pk_add_f32 v[10:11], v[10:11], v[24:25]
	ds_read2st64_b32 v[24:25], v19 offset1:4
	v_and_b32_e32 v19, 0x3d0, v17
	v_add_u32_e32 v19, 0, v19
	ds_read2st64_b32 v[26:27], v19 offset1:4
	s_waitcnt lgkmcnt(1)
	v_mov_b32_e32 v28, v24
	s_waitcnt lgkmcnt(0)
	v_mov_b32_e32 v29, v26
	v_mov_b32_e32 v26, v25
	v_pk_mul_f32 v[24:25], v[16:17], v[26:27] op_sel_hi:[0,1]
	v_add_u32_e32 v17, s30, v17
	v_and_b32_e32 v17, 0x3e0, v17
	v_pk_fma_f32 v[24:25], v[18:19], v[28:29], v[24:25] op_sel_hi:[0,1,1] neg_lo:[0,0,1] neg_hi:[0,0,1]
	v_add_u32_e32 v17, 0, v17
	v_pk_add_f32 v[12:13], v[12:13], v[24:25]
	ds_read2st64_b32 v[24:25], v17 offset1:4
	v_mul_lo_u32 v17, s30, v22
	v_and_b32_e32 v17, 0x3f0, v17
	v_add_u32_e32 v17, 0, v17
	ds_read2st64_b32 v[28:29], v17 offset1:4
	v_mov_b32_e32 v19, v16
	s_waitcnt lgkmcnt(1)
	v_mul_f32_e32 v26, v16, v25
	v_mul_f32_e32 v24, v18, v24
	s_lshl_b32 s30, s41, 9
	s_waitcnt lgkmcnt(0)
	v_pk_mul_f32 v[16:17], v[18:19], v[28:29]
	s_nop 0
	v_mov_b32_e32 v25, v16
	v_mov_b32_e32 v27, v17
	v_pk_add_f32 v[16:17], v[24:25], v[26:27] neg_lo:[0,1] neg_hi:[0,1]
	s_nop 0
	v_pk_add_f32 v[14:15], v[14:15], v[16:17]
	v_lshl_add_u64 v[16:17], s[30:31], 2, v[6:7]
	s_nop 0
	s_lshl_b32 s30, s41, 2
	v_mul_lo_u32 v17, s30, v21
	v_and_b32_e32 v19, 0x3e0, v17
	v_add_u32_e32 v19, 0, v19
	v_add_u32_e32 v17, s30, v17
	ds_read2st64_b32 v[24:25], v19 offset1:4
	v_and_b32_e32 v19, 0x3f4, v17
	v_add_u32_e32 v19, 0, v19
	ds_read2st64_b32 v[26:27], v19 offset1:4
	s_or_b32 s41, s40, 6
	s_waitcnt lgkmcnt(0)
	v_mov_b32_e32 v28, v24
	v_mov_b32_e32 v29, v26
	v_mov_b32_e32 v26, v25
	s_waitcnt vmcnt(20)
	v_mov_b32_e32 v18, v50
	v_mov_b32_e32 v16, v51
	v_pk_mul_f32 v[24:25], v[16:17], v[26:27] op_sel_hi:[0,1]
	v_add_u32_e32 v17, s30, v17
	v_pk_fma_f32 v[24:25], v[18:19], v[28:29], v[24:25] op_sel_hi:[0,1,1] neg_lo:[0,0,1] neg_hi:[0,0,1]
	v_and_b32_e32 v19, 0x3e8, v17
	v_add_u32_e32 v19, 0, v19
	v_add_u32_e32 v17, s30, v17
	v_pk_add_f32 v[8:9], v[8:9], v[24:25]
	ds_read2st64_b32 v[24:25], v19 offset1:4
	v_and_b32_e32 v19, 0x3fc, v17
	v_add_u32_e32 v19, 0, v19
	ds_read2st64_b32 v[26:27], v19 offset1:4
	s_waitcnt lgkmcnt(1)
	v_mov_b32_e32 v28, v24
	s_waitcnt lgkmcnt(0)
	v_mov_b32_e32 v29, v26
	v_mov_b32_e32 v26, v25
	v_pk_mul_f32 v[24:25], v[16:17], v[26:27] op_sel_hi:[0,1]
	v_add_u32_e32 v17, s30, v17
	v_pk_fma_f32 v[24:25], v[18:19], v[28:29], v[24:25] op_sel_hi:[0,1,1] neg_lo:[0,0,1] neg_hi:[0,0,1]
	v_and_b32_e32 v19, 0x3f0, v17
	v_add_u32_e32 v19, 0, v19
	v_add_u32_e32 v17, s30, v17
	v_pk_add_f32 v[10:11], v[10:11], v[24:25]
	ds_read2st64_b32 v[24:25], v19 offset1:4
	v_and_b32_e32 v19, 0x3e4, v17
	v_add_u32_e32 v19, 0, v19
	ds_read2st64_b32 v[26:27], v19 offset1:4
	s_waitcnt lgkmcnt(1)
	v_mov_b32_e32 v28, v24
	s_waitcnt lgkmcnt(0)
	v_mov_b32_e32 v29, v26
	v_mov_b32_e32 v26, v25
	v_pk_mul_f32 v[24:25], v[16:17], v[26:27] op_sel_hi:[0,1]
	v_add_u32_e32 v17, s30, v17
	v_and_b32_e32 v17, 0x3f8, v17
	v_pk_fma_f32 v[24:25], v[18:19], v[28:29], v[24:25] op_sel_hi:[0,1,1] neg_lo:[0,0,1] neg_hi:[0,0,1]
	v_add_u32_e32 v17, 0, v17
	v_pk_add_f32 v[12:13], v[12:13], v[24:25]
	ds_read2st64_b32 v[24:25], v17 offset1:4
	v_mul_lo_u32 v17, s30, v22
	v_and_b32_e32 v17, 0x3ec, v17
	v_add_u32_e32 v17, 0, v17
	ds_read2st64_b32 v[28:29], v17 offset1:4
	v_mov_b32_e32 v19, v16
	s_waitcnt lgkmcnt(1)
	v_mul_f32_e32 v26, v16, v25
	v_mul_f32_e32 v24, v18, v24
	s_lshl_b32 s30, s41, 9
	s_waitcnt lgkmcnt(0)
	v_pk_mul_f32 v[16:17], v[18:19], v[28:29]
	s_nop 0
	v_mov_b32_e32 v25, v16
	v_mov_b32_e32 v27, v17
	v_pk_add_f32 v[16:17], v[24:25], v[26:27] neg_lo:[0,1] neg_hi:[0,1]
	s_nop 0
	v_pk_add_f32 v[14:15], v[14:15], v[16:17]
	v_lshl_add_u64 v[16:17], s[30:31], 2, v[6:7]
	s_nop 0
	s_lshl_b32 s30, s41, 2
	v_mul_lo_u32 v17, s30, v21
	v_and_b32_e32 v19, 0x3c0, v17
	v_add_u32_e32 v19, 0, v19
	v_add_u32_e32 v17, s30, v17
	ds_read2st64_b32 v[24:25], v19 offset1:4
	v_and_b32_e32 v19, 0x3d8, v17
	v_add_u32_e32 v19, 0, v19
	ds_read2st64_b32 v[26:27], v19 offset1:4
	s_or_b32 s41, s40, 7
	s_waitcnt lgkmcnt(0)
	v_mov_b32_e32 v28, v24
	v_mov_b32_e32 v29, v26
	v_mov_b32_e32 v26, v25
	s_waitcnt vmcnt(18)
	v_mov_b32_e32 v18, v52
	v_mov_b32_e32 v16, v53
	v_pk_mul_f32 v[24:25], v[16:17], v[26:27] op_sel_hi:[0,1]
	v_add_u32_e32 v17, s30, v17
	v_pk_fma_f32 v[24:25], v[18:19], v[28:29], v[24:25] op_sel_hi:[0,1,1] neg_lo:[0,0,1] neg_hi:[0,0,1]
	v_and_b32_e32 v19, 0x3f0, v17
	v_add_u32_e32 v19, 0, v19
	v_add_u32_e32 v17, s30, v17
	v_pk_add_f32 v[8:9], v[8:9], v[24:25]
	ds_read2st64_b32 v[24:25], v19 offset1:4
	v_and_b32_e32 v19, 0x3c8, v17
	v_add_u32_e32 v19, 0, v19
	ds_read2st64_b32 v[26:27], v19 offset1:4
	s_waitcnt lgkmcnt(1)
	v_mov_b32_e32 v28, v24
	s_waitcnt lgkmcnt(0)
	v_mov_b32_e32 v29, v26
	v_mov_b32_e32 v26, v25
	v_pk_mul_f32 v[24:25], v[16:17], v[26:27] op_sel_hi:[0,1]
	v_add_u32_e32 v17, s30, v17
	v_pk_fma_f32 v[24:25], v[18:19], v[28:29], v[24:25] op_sel_hi:[0,1,1] neg_lo:[0,0,1] neg_hi:[0,0,1]
	v_and_b32_e32 v19, 0x3e0, v17
	v_add_u32_e32 v19, 0, v19
	v_add_u32_e32 v17, s30, v17
	v_pk_add_f32 v[10:11], v[10:11], v[24:25]
	ds_read2st64_b32 v[24:25], v19 offset1:4
	v_and_b32_e32 v19, 0x3f8, v17
	v_add_u32_e32 v19, 0, v19
	ds_read2st64_b32 v[26:27], v19 offset1:4
	s_waitcnt lgkmcnt(1)
	v_mov_b32_e32 v28, v24
	s_waitcnt lgkmcnt(0)
	v_mov_b32_e32 v29, v26
	v_mov_b32_e32 v26, v25
	v_pk_mul_f32 v[24:25], v[16:17], v[26:27] op_sel_hi:[0,1]
	v_add_u32_e32 v17, s30, v17
	v_and_b32_e32 v17, 0x3d0, v17
	v_pk_fma_f32 v[24:25], v[18:19], v[28:29], v[24:25] op_sel_hi:[0,1,1] neg_lo:[0,0,1] neg_hi:[0,0,1]
	v_add_u32_e32 v17, 0, v17
	v_pk_add_f32 v[12:13], v[12:13], v[24:25]
	ds_read2st64_b32 v[24:25], v17 offset1:4
	v_mul_lo_u32 v17, s30, v22
	v_and_b32_e32 v17, 0x3e8, v17
	v_add_u32_e32 v17, 0, v17
	ds_read2st64_b32 v[28:29], v17 offset1:4
	v_mov_b32_e32 v19, v16
	s_waitcnt lgkmcnt(1)
	v_mul_f32_e32 v26, v16, v25
	v_mul_f32_e32 v24, v18, v24
	s_lshl_b32 s30, s41, 9
	s_waitcnt lgkmcnt(0)
	v_pk_mul_f32 v[16:17], v[18:19], v[28:29]
	s_nop 0
	v_mov_b32_e32 v25, v16
	v_mov_b32_e32 v27, v17
	v_pk_add_f32 v[16:17], v[24:25], v[26:27] neg_lo:[0,1] neg_hi:[0,1]
	s_nop 0
	v_pk_add_f32 v[14:15], v[14:15], v[16:17]
	v_lshl_add_u64 v[16:17], s[30:31], 2, v[6:7]
	s_nop 0
	s_lshl_b32 s30, s41, 2
	v_mul_lo_u32 v17, s30, v21
	v_and_b32_e32 v19, 0x3e0, v17
	v_add_u32_e32 v19, 0, v19
	v_add_u32_e32 v17, s30, v17
	ds_read2st64_b32 v[24:25], v19 offset1:4
	v_and_b32_e32 v19, 0x3fc, v17
	v_add_u32_e32 v19, 0, v19
	ds_read2st64_b32 v[26:27], v19 offset1:4
	s_or_b32 s41, s40, 8
	s_waitcnt lgkmcnt(0)
	v_mov_b32_e32 v28, v24
	v_mov_b32_e32 v29, v26
	v_mov_b32_e32 v26, v25
	s_waitcnt vmcnt(16)
	v_mov_b32_e32 v18, v54
	v_mov_b32_e32 v16, v55
	v_pk_mul_f32 v[24:25], v[16:17], v[26:27] op_sel_hi:[0,1]
	v_add_u32_e32 v17, s30, v17
	v_pk_fma_f32 v[24:25], v[18:19], v[28:29], v[24:25] op_sel_hi:[0,1,1] neg_lo:[0,0,1] neg_hi:[0,0,1]
	v_and_b32_e32 v19, 0x3f8, v17
	v_add_u32_e32 v19, 0, v19
	v_add_u32_e32 v17, s30, v17
	v_pk_add_f32 v[8:9], v[8:9], v[24:25]
	ds_read2st64_b32 v[24:25], v19 offset1:4
	v_and_b32_e32 v19, 0x3f4, v17
	v_add_u32_e32 v19, 0, v19
	ds_read2st64_b32 v[26:27], v19 offset1:4
	s_waitcnt lgkmcnt(1)
	v_mov_b32_e32 v28, v24
	s_waitcnt lgkmcnt(0)
	v_mov_b32_e32 v29, v26
	v_mov_b32_e32 v26, v25
	v_pk_mul_f32 v[24:25], v[16:17], v[26:27] op_sel_hi:[0,1]
	v_add_u32_e32 v17, s30, v17
	v_pk_fma_f32 v[24:25], v[18:19], v[28:29], v[24:25] op_sel_hi:[0,1,1] neg_lo:[0,0,1] neg_hi:[0,0,1]
	v_and_b32_e32 v19, 0x3f0, v17
	v_add_u32_e32 v19, 0, v19
	v_add_u32_e32 v17, s30, v17
	v_pk_add_f32 v[10:11], v[10:11], v[24:25]
	ds_read2st64_b32 v[24:25], v19 offset1:4
	v_and_b32_e32 v19, 0x3ec, v17
	v_add_u32_e32 v19, 0, v19
	ds_read2st64_b32 v[26:27], v19 offset1:4
	s_waitcnt lgkmcnt(1)
	v_mov_b32_e32 v28, v24
	s_waitcnt lgkmcnt(0)
	v_mov_b32_e32 v29, v26
	v_mov_b32_e32 v26, v25
	v_pk_mul_f32 v[24:25], v[16:17], v[26:27] op_sel_hi:[0,1]
	v_add_u32_e32 v17, s30, v17
	v_and_b32_e32 v17, 0x3e8, v17
	v_pk_fma_f32 v[24:25], v[18:19], v[28:29], v[24:25] op_sel_hi:[0,1,1] neg_lo:[0,0,1] neg_hi:[0,0,1]
	v_add_u32_e32 v17, 0, v17
	v_pk_add_f32 v[12:13], v[12:13], v[24:25]
	ds_read2st64_b32 v[24:25], v17 offset1:4
	v_mul_lo_u32 v17, s30, v22
	v_and_b32_e32 v17, 0x3e4, v17
	v_add_u32_e32 v17, 0, v17
	ds_read2st64_b32 v[28:29], v17 offset1:4
	v_mov_b32_e32 v19, v16
	s_waitcnt lgkmcnt(1)
	v_mul_f32_e32 v26, v16, v25
	v_mul_f32_e32 v24, v18, v24
	s_lshl_b32 s30, s41, 9
	s_waitcnt lgkmcnt(0)
	v_pk_mul_f32 v[16:17], v[18:19], v[28:29]
	s_nop 0
	v_mov_b32_e32 v25, v16
	v_mov_b32_e32 v27, v17
	v_pk_add_f32 v[16:17], v[24:25], v[26:27] neg_lo:[0,1] neg_hi:[0,1]
	s_nop 0
	v_pk_add_f32 v[14:15], v[14:15], v[16:17]
	v_lshl_add_u64 v[16:17], s[30:31], 2, v[6:7]
	s_nop 0
	s_lshl_b32 s30, s41, 2
	v_mul_lo_u32 v17, s30, v21
	v_and_b32_e32 v19, 0x300, v17
	v_add_u32_e32 v19, 0, v19
	v_add_u32_e32 v17, s30, v17
	ds_read2st64_b32 v[24:25], v19 offset1:4
	v_and_b32_e32 v19, 0x3e0, v17
	v_add_u32_e32 v19, 0, v19
	ds_read2st64_b32 v[26:27], v19 offset1:4
	s_or_b32 s41, s40, 9
	s_waitcnt lgkmcnt(0)
	v_mov_b32_e32 v28, v24
	v_mov_b32_e32 v29, v26
	v_mov_b32_e32 v26, v25
	s_waitcnt vmcnt(14)
	v_mov_b32_e32 v18, v56
	v_mov_b32_e32 v16, v57
	v_pk_mul_f32 v[24:25], v[16:17], v[26:27] op_sel_hi:[0,1]
	v_add_u32_e32 v17, s30, v17
	v_pk_fma_f32 v[24:25], v[18:19], v[28:29], v[24:25] op_sel_hi:[0,1,1] neg_lo:[0,0,1] neg_hi:[0,0,1]
	v_and_b32_e32 v19, 0x3c0, v17
	v_add_u32_e32 v19, 0, v19
	v_add_u32_e32 v17, s30, v17
	v_pk_add_f32 v[8:9], v[8:9], v[24:25]
	ds_read2st64_b32 v[24:25], v19 offset1:4
	v_and_b32_e32 v19, 0x3e0, v17
	v_add_u32_e32 v19, 0, v19
	ds_read2st64_b32 v[26:27], v19 offset1:4
	s_waitcnt lgkmcnt(1)
	v_mov_b32_e32 v28, v24
	s_waitcnt lgkmcnt(0)
	v_mov_b32_e32 v29, v26
	v_mov_b32_e32 v26, v25
	v_pk_mul_f32 v[24:25], v[16:17], v[26:27] op_sel_hi:[0,1]
	v_add_u32_e32 v17, s30, v17
	v_pk_fma_f32 v[24:25], v[18:19], v[28:29], v[24:25] op_sel_hi:[0,1,1] neg_lo:[0,0,1] neg_hi:[0,0,1]
	v_and_b32_e32 v19, 0x380, v17
	v_add_u32_e32 v19, 0, v19
	v_add_u32_e32 v17, s30, v17
	v_pk_add_f32 v[10:11], v[10:11], v[24:25]
	ds_read2st64_b32 v[24:25], v19 offset1:4
	v_and_b32_e32 v19, 0x3e0, v17
	v_add_u32_e32 v19, 0, v19
	ds_read2st64_b32 v[26:27], v19 offset1:4
	s_waitcnt lgkmcnt(1)
	v_mov_b32_e32 v28, v24
	s_waitcnt lgkmcnt(0)
	v_mov_b32_e32 v29, v26
	v_mov_b32_e32 v26, v25
	v_pk_mul_f32 v[24:25], v[16:17], v[26:27] op_sel_hi:[0,1]
	v_add_u32_e32 v17, s30, v17
	v_and_b32_e32 v17, 0x3c0, v17
	v_pk_fma_f32 v[24:25], v[18:19], v[28:29], v[24:25] op_sel_hi:[0,1,1] neg_lo:[0,0,1] neg_hi:[0,0,1]
	v_add_u32_e32 v17, 0, v17
	v_pk_add_f32 v[12:13], v[12:13], v[24:25]
	ds_read2st64_b32 v[24:25], v17 offset1:4
	v_mul_lo_u32 v17, s30, v22
	v_and_b32_e32 v17, 0x3e0, v17
	v_add_u32_e32 v17, 0, v17
	ds_read2st64_b32 v[28:29], v17 offset1:4
	v_mov_b32_e32 v19, v16
	s_waitcnt lgkmcnt(1)
	v_mul_f32_e32 v26, v16, v25
	v_mul_f32_e32 v24, v18, v24
	s_lshl_b32 s30, s41, 9
	s_waitcnt lgkmcnt(0)
	v_pk_mul_f32 v[16:17], v[18:19], v[28:29]
	s_nop 0
	v_mov_b32_e32 v25, v16
	v_mov_b32_e32 v27, v17
	v_pk_add_f32 v[16:17], v[24:25], v[26:27] neg_lo:[0,1] neg_hi:[0,1]
	s_nop 0
	v_pk_add_f32 v[14:15], v[14:15], v[16:17]
	v_lshl_add_u64 v[16:17], s[30:31], 2, v[6:7]
	s_nop 0
	s_lshl_b32 s30, s41, 2
	v_mul_lo_u32 v17, s30, v21
	v_and_b32_e32 v19, 0x3e0, v17
	v_add_u32_e32 v19, 0, v19
	v_add_u32_e32 v17, s30, v17
	ds_read2st64_b32 v[24:25], v19 offset1:4
	v_and_b32_e32 v19, 0x3e4, v17
	v_add_u32_e32 v19, 0, v19
	ds_read2st64_b32 v[26:27], v19 offset1:4
	s_or_b32 s41, s40, 10
	s_waitcnt lgkmcnt(0)
	v_mov_b32_e32 v28, v24
	v_mov_b32_e32 v29, v26
	v_mov_b32_e32 v26, v25
	s_waitcnt vmcnt(12)
	v_mov_b32_e32 v18, v58
	v_mov_b32_e32 v16, v59
	v_pk_mul_f32 v[24:25], v[16:17], v[26:27] op_sel_hi:[0,1]
	v_add_u32_e32 v17, s30, v17
	v_pk_fma_f32 v[24:25], v[18:19], v[28:29], v[24:25] op_sel_hi:[0,1,1] neg_lo:[0,0,1] neg_hi:[0,0,1]
	v_and_b32_e32 v19, 0x3e8, v17
	v_add_u32_e32 v19, 0, v19
	v_add_u32_e32 v17, s30, v17
	v_pk_add_f32 v[8:9], v[8:9], v[24:25]
	ds_read2st64_b32 v[24:25], v19 offset1:4
	v_and_b32_e32 v19, 0x3ec, v17
	v_add_u32_e32 v19, 0, v19
	ds_read2st64_b32 v[26:27], v19 offset1:4
	s_waitcnt lgkmcnt(1)
	v_mov_b32_e32 v28, v24
	s_waitcnt lgkmcnt(0)
	v_mov_b32_e32 v29, v26
	v_mov_b32_e32 v26, v25
	v_pk_mul_f32 v[24:25], v[16:17], v[26:27] op_sel_hi:[0,1]
	v_add_u32_e32 v17, s30, v17
	v_pk_fma_f32 v[24:25], v[18:19], v[28:29], v[24:25] op_sel_hi:[0,1,1] neg_lo:[0,0,1] neg_hi:[0,0,1]
	v_and_b32_e32 v19, 0x3f0, v17
	v_add_u32_e32 v19, 0, v19
	v_add_u32_e32 v17, s30, v17
	v_pk_add_f32 v[10:11], v[10:11], v[24:25]
	ds_read2st64_b32 v[24:25], v19 offset1:4
	v_and_b32_e32 v19, 0x3f4, v17
	v_add_u32_e32 v19, 0, v19
	ds_read2st64_b32 v[26:27], v19 offset1:4
	s_waitcnt lgkmcnt(1)
	v_mov_b32_e32 v28, v24
	s_waitcnt lgkmcnt(0)
	v_mov_b32_e32 v29, v26
	v_mov_b32_e32 v26, v25
	v_pk_mul_f32 v[24:25], v[16:17], v[26:27] op_sel_hi:[0,1]
	v_add_u32_e32 v17, s30, v17
	v_and_b32_e32 v17, 0x3f8, v17
	v_pk_fma_f32 v[24:25], v[18:19], v[28:29], v[24:25] op_sel_hi:[0,1,1] neg_lo:[0,0,1] neg_hi:[0,0,1]
	v_add_u32_e32 v17, 0, v17
	v_pk_add_f32 v[12:13], v[12:13], v[24:25]
	ds_read2st64_b32 v[24:25], v17 offset1:4
	v_mul_lo_u32 v17, s30, v22
	v_and_b32_e32 v17, 0x3fc, v17
	v_add_u32_e32 v17, 0, v17
	ds_read2st64_b32 v[28:29], v17 offset1:4
	v_mov_b32_e32 v19, v16
	s_waitcnt lgkmcnt(1)
	v_mul_f32_e32 v26, v16, v25
	v_mul_f32_e32 v24, v18, v24
	s_lshl_b32 s30, s41, 9
	s_waitcnt lgkmcnt(0)
	v_pk_mul_f32 v[16:17], v[18:19], v[28:29]
	s_nop 0
	v_mov_b32_e32 v25, v16
	v_mov_b32_e32 v27, v17
	v_pk_add_f32 v[16:17], v[24:25], v[26:27] neg_lo:[0,1] neg_hi:[0,1]
	s_nop 0
	v_pk_add_f32 v[14:15], v[14:15], v[16:17]
	v_lshl_add_u64 v[16:17], s[30:31], 2, v[6:7]
	s_nop 0
	s_lshl_b32 s30, s41, 2
	v_mul_lo_u32 v17, s30, v21
	v_and_b32_e32 v19, 0x3c0, v17
	v_add_u32_e32 v19, 0, v19
	v_add_u32_e32 v17, s30, v17
	ds_read2st64_b32 v[24:25], v19 offset1:4
	v_and_b32_e32 v19, 0x3e8, v17
	v_add_u32_e32 v19, 0, v19
	ds_read2st64_b32 v[26:27], v19 offset1:4
	s_or_b32 s41, s40, 11
	s_waitcnt lgkmcnt(0)
	v_mov_b32_e32 v28, v24
	v_mov_b32_e32 v29, v26
	v_mov_b32_e32 v26, v25
	s_waitcnt vmcnt(10)
	v_mov_b32_e32 v18, v60
	v_mov_b32_e32 v16, v61
	v_pk_mul_f32 v[24:25], v[16:17], v[26:27] op_sel_hi:[0,1]
	v_add_u32_e32 v17, s30, v17
	v_pk_fma_f32 v[24:25], v[18:19], v[28:29], v[24:25] op_sel_hi:[0,1,1] neg_lo:[0,0,1] neg_hi:[0,0,1]
	v_and_b32_e32 v19, 0x3d0, v17
	v_add_u32_e32 v19, 0, v19
	v_add_u32_e32 v17, s30, v17
	v_pk_add_f32 v[8:9], v[8:9], v[24:25]
	ds_read2st64_b32 v[24:25], v19 offset1:4
	v_and_b32_e32 v19, 0x3f8, v17
	v_add_u32_e32 v19, 0, v19
	ds_read2st64_b32 v[26:27], v19 offset1:4
	s_waitcnt lgkmcnt(1)
	v_mov_b32_e32 v28, v24
	s_waitcnt lgkmcnt(0)
	v_mov_b32_e32 v29, v26
	v_mov_b32_e32 v26, v25
	v_pk_mul_f32 v[24:25], v[16:17], v[26:27] op_sel_hi:[0,1]
	v_add_u32_e32 v17, s30, v17
	v_pk_fma_f32 v[24:25], v[18:19], v[28:29], v[24:25] op_sel_hi:[0,1,1] neg_lo:[0,0,1] neg_hi:[0,0,1]
	v_and_b32_e32 v19, 0x3e0, v17
	v_add_u32_e32 v19, 0, v19
	v_add_u32_e32 v17, s30, v17
	v_pk_add_f32 v[10:11], v[10:11], v[24:25]
	ds_read2st64_b32 v[24:25], v19 offset1:4
	v_and_b32_e32 v19, 0x3c8, v17
	v_add_u32_e32 v19, 0, v19
	ds_read2st64_b32 v[26:27], v19 offset1:4
	s_waitcnt lgkmcnt(1)
	v_mov_b32_e32 v28, v24
	s_waitcnt lgkmcnt(0)
	v_mov_b32_e32 v29, v26
	v_mov_b32_e32 v26, v25
	v_pk_mul_f32 v[24:25], v[16:17], v[26:27] op_sel_hi:[0,1]
	v_add_u32_e32 v17, s30, v17
	v_and_b32_e32 v17, 0x3f0, v17
	v_pk_fma_f32 v[24:25], v[18:19], v[28:29], v[24:25] op_sel_hi:[0,1,1] neg_lo:[0,0,1] neg_hi:[0,0,1]
	v_add_u32_e32 v17, 0, v17
	v_pk_add_f32 v[12:13], v[12:13], v[24:25]
	ds_read2st64_b32 v[24:25], v17 offset1:4
	v_mul_lo_u32 v17, s30, v22
	v_and_b32_e32 v17, 0x3d8, v17
	v_add_u32_e32 v17, 0, v17
	ds_read2st64_b32 v[28:29], v17 offset1:4
	v_mov_b32_e32 v19, v16
	s_waitcnt lgkmcnt(1)
	v_mul_f32_e32 v26, v16, v25
	v_mul_f32_e32 v24, v18, v24
	s_lshl_b32 s30, s41, 9
	s_waitcnt lgkmcnt(0)
	v_pk_mul_f32 v[16:17], v[18:19], v[28:29]
	s_nop 0
	v_mov_b32_e32 v25, v16
	v_mov_b32_e32 v27, v17
	v_pk_add_f32 v[16:17], v[24:25], v[26:27] neg_lo:[0,1] neg_hi:[0,1]
	s_nop 0
	v_pk_add_f32 v[14:15], v[14:15], v[16:17]
	v_lshl_add_u64 v[16:17], s[30:31], 2, v[6:7]
	s_nop 0
	s_lshl_b32 s30, s41, 2
	v_mul_lo_u32 v17, s30, v21
	v_and_b32_e32 v19, 0x3e0, v17
	v_add_u32_e32 v19, 0, v19
	v_add_u32_e32 v17, s30, v17
	ds_read2st64_b32 v[24:25], v19 offset1:4
	v_and_b32_e32 v19, 0x3ec, v17
	v_add_u32_e32 v19, 0, v19
	ds_read2st64_b32 v[26:27], v19 offset1:4
	s_or_b32 s41, s40, 12
	s_waitcnt lgkmcnt(0)
	v_mov_b32_e32 v28, v24
	v_mov_b32_e32 v29, v26
	v_mov_b32_e32 v26, v25
	s_waitcnt vmcnt(8)
	v_mov_b32_e32 v18, v62
	v_mov_b32_e32 v16, v63
	v_pk_mul_f32 v[24:25], v[16:17], v[26:27] op_sel_hi:[0,1]
	v_add_u32_e32 v17, s30, v17
	v_pk_fma_f32 v[24:25], v[18:19], v[28:29], v[24:25] op_sel_hi:[0,1,1] neg_lo:[0,0,1] neg_hi:[0,0,1]
	v_and_b32_e32 v19, 0x3f8, v17
	v_add_u32_e32 v19, 0, v19
	v_add_u32_e32 v17, s30, v17
	v_pk_add_f32 v[8:9], v[8:9], v[24:25]
	ds_read2st64_b32 v[24:25], v19 offset1:4
	v_and_b32_e32 v19, 0x3e4, v17
	v_add_u32_e32 v19, 0, v19
	ds_read2st64_b32 v[26:27], v19 offset1:4
	s_waitcnt lgkmcnt(1)
	v_mov_b32_e32 v28, v24
	s_waitcnt lgkmcnt(0)
	v_mov_b32_e32 v29, v26
	v_mov_b32_e32 v26, v25
	v_pk_mul_f32 v[24:25], v[16:17], v[26:27] op_sel_hi:[0,1]
	v_add_u32_e32 v17, s30, v17
	v_pk_fma_f32 v[24:25], v[18:19], v[28:29], v[24:25] op_sel_hi:[0,1,1] neg_lo:[0,0,1] neg_hi:[0,0,1]
	v_and_b32_e32 v19, 0x3f0, v17
	v_add_u32_e32 v19, 0, v19
	v_add_u32_e32 v17, s30, v17
	v_pk_add_f32 v[10:11], v[10:11], v[24:25]
	ds_read2st64_b32 v[24:25], v19 offset1:4
	v_and_b32_e32 v19, 0x3fc, v17
	v_add_u32_e32 v19, 0, v19
	ds_read2st64_b32 v[26:27], v19 offset1:4
	s_waitcnt lgkmcnt(1)
	v_mov_b32_e32 v28, v24
	s_waitcnt lgkmcnt(0)
	v_mov_b32_e32 v29, v26
	v_mov_b32_e32 v26, v25
	v_pk_mul_f32 v[24:25], v[16:17], v[26:27] op_sel_hi:[0,1]
	v_add_u32_e32 v17, s30, v17
	v_and_b32_e32 v17, 0x3e8, v17
	v_pk_fma_f32 v[24:25], v[18:19], v[28:29], v[24:25] op_sel_hi:[0,1,1] neg_lo:[0,0,1] neg_hi:[0,0,1]
	v_add_u32_e32 v17, 0, v17
	v_pk_add_f32 v[12:13], v[12:13], v[24:25]
	ds_read2st64_b32 v[24:25], v17 offset1:4
	v_mul_lo_u32 v17, s30, v22
	v_and_b32_e32 v17, 0x3f4, v17
	v_add_u32_e32 v17, 0, v17
	ds_read2st64_b32 v[28:29], v17 offset1:4
	v_mov_b32_e32 v19, v16
	s_waitcnt lgkmcnt(1)
	v_mul_f32_e32 v26, v16, v25
	v_mul_f32_e32 v24, v18, v24
	s_lshl_b32 s30, s41, 9
	s_waitcnt lgkmcnt(0)
	v_pk_mul_f32 v[16:17], v[18:19], v[28:29]
	s_nop 0
	v_mov_b32_e32 v25, v16
	v_mov_b32_e32 v27, v17
	v_pk_add_f32 v[16:17], v[24:25], v[26:27] neg_lo:[0,1] neg_hi:[0,1]
	s_nop 0
	v_pk_add_f32 v[14:15], v[14:15], v[16:17]
	v_lshl_add_u64 v[16:17], s[30:31], 2, v[6:7]
	s_nop 0
	s_lshl_b32 s30, s41, 2
	v_mul_lo_u32 v17, s30, v21
	v_and_b32_e32 v19, 0x380, v17
	v_add_u32_e32 v19, 0, v19
	v_add_u32_e32 v17, s30, v17
	ds_read2st64_b32 v[24:25], v19 offset1:4
	v_and_b32_e32 v19, 0x3f0, v17
	v_add_u32_e32 v19, 0, v19
	ds_read2st64_b32 v[26:27], v19 offset1:4
	s_or_b32 s41, s40, 13
	s_waitcnt lgkmcnt(0)
	v_mov_b32_e32 v28, v24
	v_mov_b32_e32 v29, v26
	v_mov_b32_e32 v26, v25
	s_waitcnt vmcnt(6)
	v_mov_b32_e32 v18, v64
	v_mov_b32_e32 v16, v65
	v_pk_mul_f32 v[24:25], v[16:17], v[26:27] op_sel_hi:[0,1]
	v_add_u32_e32 v17, s30, v17
	v_pk_fma_f32 v[24:25], v[18:19], v[28:29], v[24:25] op_sel_hi:[0,1,1] neg_lo:[0,0,1] neg_hi:[0,0,1]
	v_and_b32_e32 v19, 0x3e0, v17
	v_add_u32_e32 v19, 0, v19
	v_add_u32_e32 v17, s30, v17
	v_pk_add_f32 v[8:9], v[8:9], v[24:25]
	ds_read2st64_b32 v[24:25], v19 offset1:4
	v_and_b32_e32 v19, 0x3d0, v17
	v_add_u32_e32 v19, 0, v19
	ds_read2st64_b32 v[26:27], v19 offset1:4
	s_waitcnt lgkmcnt(1)
	v_mov_b32_e32 v28, v24
	s_waitcnt lgkmcnt(0)
	v_mov_b32_e32 v29, v26
	v_mov_b32_e32 v26, v25
	v_pk_mul_f32 v[24:25], v[16:17], v[26:27] op_sel_hi:[0,1]
	v_add_u32_e32 v17, s30, v17
	v_pk_fma_f32 v[24:25], v[18:19], v[28:29], v[24:25] op_sel_hi:[0,1,1] neg_lo:[0,0,1] neg_hi:[0,0,1]
	v_and_b32_e32 v19, 0x3c0, v17
	v_add_u32_e32 v19, 0, v19
	v_add_u32_e32 v17, s30, v17
	v_pk_add_f32 v[10:11], v[10:11], v[24:25]
	ds_read2st64_b32 v[24:25], v19 offset1:4
	v_and_b32_e32 v19, 0x3f0, v17
	v_add_u32_e32 v19, 0, v19
	ds_read2st64_b32 v[26:27], v19 offset1:4
	s_waitcnt lgkmcnt(1)
	v_mov_b32_e32 v28, v24
	s_waitcnt lgkmcnt(0)
	v_mov_b32_e32 v29, v26
	v_mov_b32_e32 v26, v25
	v_pk_mul_f32 v[24:25], v[16:17], v[26:27] op_sel_hi:[0,1]
	v_add_u32_e32 v17, s30, v17
	v_and_b32_e32 v17, 0x3a0, v17
	v_pk_fma_f32 v[24:25], v[18:19], v[28:29], v[24:25] op_sel_hi:[0,1,1] neg_lo:[0,0,1] neg_hi:[0,0,1]
	v_add_u32_e32 v17, 0, v17
	v_pk_add_f32 v[12:13], v[12:13], v[24:25]
	ds_read2st64_b32 v[24:25], v17 offset1:4
	v_mul_lo_u32 v17, s30, v22
	v_and_b32_e32 v17, 0x3d0, v17
	v_add_u32_e32 v17, 0, v17
	ds_read2st64_b32 v[28:29], v17 offset1:4
	v_mov_b32_e32 v19, v16
	s_waitcnt lgkmcnt(1)
	v_mul_f32_e32 v26, v16, v25
	v_mul_f32_e32 v24, v18, v24
	s_lshl_b32 s30, s41, 9
	s_waitcnt lgkmcnt(0)
	v_pk_mul_f32 v[16:17], v[18:19], v[28:29]
	s_nop 0
	v_mov_b32_e32 v25, v16
	v_mov_b32_e32 v27, v17
	v_pk_add_f32 v[16:17], v[24:25], v[26:27] neg_lo:[0,1] neg_hi:[0,1]
	s_nop 0
	v_pk_add_f32 v[14:15], v[14:15], v[16:17]
	v_lshl_add_u64 v[16:17], s[30:31], 2, v[6:7]
	s_nop 0
	s_lshl_b32 s30, s41, 2
	v_mul_lo_u32 v17, s30, v21
	v_and_b32_e32 v19, 0x3e0, v17
	v_add_u32_e32 v19, 0, v19
	v_add_u32_e32 v17, s30, v17
	ds_read2st64_b32 v[24:25], v19 offset1:4
	v_and_b32_e32 v19, 0x3f4, v17
	v_add_u32_e32 v19, 0, v19
	ds_read2st64_b32 v[26:27], v19 offset1:4
	s_or_b32 s41, s40, 14
	s_waitcnt lgkmcnt(0)
	v_mov_b32_e32 v28, v24
	v_mov_b32_e32 v29, v26
	v_mov_b32_e32 v26, v25
	s_waitcnt vmcnt(4)
	v_mov_b32_e32 v18, v66
	v_mov_b32_e32 v16, v67
	v_pk_mul_f32 v[24:25], v[16:17], v[26:27] op_sel_hi:[0,1]
	v_add_u32_e32 v17, s30, v17
	v_pk_fma_f32 v[24:25], v[18:19], v[28:29], v[24:25] op_sel_hi:[0,1,1] neg_lo:[0,0,1] neg_hi:[0,0,1]
	v_and_b32_e32 v19, 0x3e8, v17
	v_add_u32_e32 v19, 0, v19
	v_add_u32_e32 v17, s30, v17
	v_pk_add_f32 v[8:9], v[8:9], v[24:25]
	ds_read2st64_b32 v[24:25], v19 offset1:4
	v_and_b32_e32 v19, 0x3fc, v17
	v_add_u32_e32 v19, 0, v19
	ds_read2st64_b32 v[26:27], v19 offset1:4
	s_waitcnt lgkmcnt(1)
	v_mov_b32_e32 v28, v24
	s_waitcnt lgkmcnt(0)
	v_mov_b32_e32 v29, v26
	v_mov_b32_e32 v26, v25
	v_pk_mul_f32 v[24:25], v[16:17], v[26:27] op_sel_hi:[0,1]
	v_add_u32_e32 v17, s30, v17
	v_pk_fma_f32 v[24:25], v[18:19], v[28:29], v[24:25] op_sel_hi:[0,1,1] neg_lo:[0,0,1] neg_hi:[0,0,1]
	v_and_b32_e32 v19, 0x3f0, v17
	v_add_u32_e32 v19, 0, v19
	v_add_u32_e32 v17, s30, v17
	v_pk_add_f32 v[10:11], v[10:11], v[24:25]
	ds_read2st64_b32 v[24:25], v19 offset1:4
	v_and_b32_e32 v19, 0x3e4, v17
	v_add_u32_e32 v19, 0, v19
	ds_read2st64_b32 v[26:27], v19 offset1:4
	s_waitcnt lgkmcnt(1)
	v_mov_b32_e32 v28, v24
	s_waitcnt lgkmcnt(0)
	v_mov_b32_e32 v29, v26
	v_mov_b32_e32 v26, v25
	v_pk_mul_f32 v[24:25], v[16:17], v[26:27] op_sel_hi:[0,1]
	v_add_u32_e32 v17, s30, v17
	v_and_b32_e32 v17, 0x3f8, v17
	v_pk_fma_f32 v[24:25], v[18:19], v[28:29], v[24:25] op_sel_hi:[0,1,1] neg_lo:[0,0,1] neg_hi:[0,0,1]
	v_add_u32_e32 v17, 0, v17
	v_pk_add_f32 v[12:13], v[12:13], v[24:25]
	ds_read2st64_b32 v[24:25], v17 offset1:4
	v_mul_lo_u32 v17, s30, v22
	v_and_b32_e32 v17, 0x3ec, v17
	v_add_u32_e32 v17, 0, v17
	ds_read2st64_b32 v[28:29], v17 offset1:4
	v_mov_b32_e32 v19, v16
	s_waitcnt lgkmcnt(1)
	v_mul_f32_e32 v26, v16, v25
	v_mul_f32_e32 v24, v18, v24
	s_lshl_b32 s30, s41, 9
	s_waitcnt lgkmcnt(0)
	v_pk_mul_f32 v[16:17], v[18:19], v[28:29]
	s_nop 0
	v_mov_b32_e32 v25, v16
	v_mov_b32_e32 v27, v17
	v_pk_add_f32 v[16:17], v[24:25], v[26:27] neg_lo:[0,1] neg_hi:[0,1]
	s_nop 0
	v_pk_add_f32 v[14:15], v[14:15], v[16:17]
	v_lshl_add_u64 v[16:17], s[30:31], 2, v[6:7]
	s_lshl_b32 s30, s41, 2
	v_mul_lo_u32 v19, s30, v21
	v_and_b32_e32 v16, 0x3c0, v19
	v_add_u32_e32 v19, s30, v19
	v_and_b32_e32 v23, 0x3f8, v19
	v_add_u32_e32 v16, 0, v16
	v_add_u32_e32 v23, 0, v23
	ds_read2st64_b32 v[16:17], v16 offset1:4
	ds_read2st64_b32 v[26:27], v23 offset1:4
	s_or_b32 s41, s40, 15
	s_add_i32 s40, s40, 16
	s_waitcnt lgkmcnt(0)
	v_mov_b32_e32 v28, v16
	v_mov_b32_e32 v29, v26
	v_mov_b32_e32 v26, v17
	s_waitcnt vmcnt(2)
	v_mov_b32_e32 v18, v68
	v_mov_b32_e32 v24, v69
	v_pk_mul_f32 v[16:17], v[24:25], v[26:27] op_sel_hi:[0,1]
	v_pk_fma_f32 v[16:17], v[18:19], v[28:29], v[16:17] op_sel_hi:[0,1,1] neg_lo:[0,0,1] neg_hi:[0,0,1]
	v_add_u32_e32 v19, s30, v19
	v_pk_add_f32 v[8:9], v[8:9], v[16:17]
	v_and_b32_e32 v16, 0x3f0, v19
	v_add_u32_e32 v19, s30, v19
	v_and_b32_e32 v23, 0x3e8, v19
	v_add_u32_e32 v16, 0, v16
	v_add_u32_e32 v23, 0, v23
	ds_read2st64_b32 v[16:17], v16 offset1:4
	ds_read2st64_b32 v[26:27], v23 offset1:4
	s_waitcnt lgkmcnt(1)
	v_mov_b32_e32 v28, v16
	s_waitcnt lgkmcnt(0)
	v_mov_b32_e32 v29, v26
	v_mov_b32_e32 v26, v17
	v_pk_mul_f32 v[16:17], v[24:25], v[26:27] op_sel_hi:[0,1]
	v_pk_fma_f32 v[16:17], v[18:19], v[28:29], v[16:17] op_sel_hi:[0,1,1] neg_lo:[0,0,1] neg_hi:[0,0,1]
	v_add_u32_e32 v19, s30, v19
	v_pk_add_f32 v[10:11], v[10:11], v[16:17]
	v_and_b32_e32 v16, 0x3e0, v19
	v_add_u32_e32 v19, s30, v19
	v_and_b32_e32 v23, 0x3d8, v19
	v_add_u32_e32 v16, 0, v16
	v_add_u32_e32 v23, 0, v23
	ds_read2st64_b32 v[16:17], v16 offset1:4
	ds_read2st64_b32 v[26:27], v23 offset1:4
	s_waitcnt lgkmcnt(1)
	v_mov_b32_e32 v28, v16
	s_waitcnt lgkmcnt(0)
	v_mov_b32_e32 v29, v26
	v_mov_b32_e32 v26, v17
	v_pk_mul_f32 v[16:17], v[24:25], v[26:27] op_sel_hi:[0,1]
	v_pk_fma_f32 v[16:17], v[18:19], v[28:29], v[16:17] op_sel_hi:[0,1,1] neg_lo:[0,0,1] neg_hi:[0,0,1]
	v_pk_add_f32 v[16:17], v[12:13], v[16:17]
	v_add_u32_e32 v12, s30, v19
	v_and_b32_e32 v12, 0x3d0, v12
	v_add_u32_e32 v12, 0, v12
	ds_read2st64_b32 v[12:13], v12 offset1:4
	v_mov_b32_e32 v19, v24
	s_waitcnt lgkmcnt(0)
	v_mul_f32_e32 v26, v24, v13
	v_mul_lo_u32 v13, s30, v22
	v_and_b32_e32 v13, 0x3c8, v13
	v_add_u32_e32 v13, 0, v13
	ds_read2st64_b32 v[28:29], v13 offset1:4
	v_mul_f32_e32 v12, v18, v12
	s_lshl_b32 s30, s41, 9
	s_waitcnt lgkmcnt(0)
	v_pk_mul_f32 v[18:19], v[18:19], v[28:29]
	s_nop 0
	v_mov_b32_e32 v13, v18
	v_mov_b32_e32 v27, v19
	v_pk_add_f32 v[12:13], v[12:13], v[26:27] neg_lo:[0,1] neg_hi:[0,1]
	s_nop 0
	v_pk_add_f32 v[18:19], v[14:15], v[12:13]
	v_lshl_add_u64 v[12:13], s[30:31], 2, v[6:7]
	s_lshl_b32 s30, s41, 2
	v_mul_lo_u32 v14, s30, v21
	v_add_u32_e32 v23, s30, v14
	v_and_b32_e32 v12, 0x3e0, v14
	v_and_b32_e32 v14, 0x3fc, v23
	v_add_u32_e32 v12, 0, v12
	v_add_u32_e32 v14, 0, v14
	ds_read2st64_b32 v[12:13], v12 offset1:4
	ds_read2st64_b32 v[14:15], v14 offset1:4
	s_cmpk_eq_i32 s40, 0x100
	s_waitcnt lgkmcnt(0)
	v_mov_b32_e32 v28, v12
	v_mov_b32_e32 v29, v14
	v_mov_b32_e32 v14, v13
	s_waitcnt vmcnt(0)
	v_mov_b32_e32 v24, v70
	v_mov_b32_e32 v26, v71
	v_pk_mul_f32 v[12:13], v[26:27], v[14:15] op_sel_hi:[0,1]
	v_pk_fma_f32 v[12:13], v[24:25], v[28:29], v[12:13] op_sel_hi:[0,1,1] neg_lo:[0,0,1] neg_hi:[0,0,1]
	v_pk_add_f32 v[14:15], v[8:9], v[12:13]
	v_add_u32_e32 v12, s30, v23
	v_add_u32_e32 v23, s30, v12
	v_and_b32_e32 v8, 0x3f8, v12
	v_and_b32_e32 v12, 0x3f4, v23
	v_add_u32_e32 v8, 0, v8
	v_add_u32_e32 v12, 0, v12
	ds_read2st64_b32 v[8:9], v8 offset1:4
	ds_read2st64_b32 v[12:13], v12 offset1:4
	s_waitcnt lgkmcnt(1)
	v_mov_b32_e32 v28, v8
	s_waitcnt lgkmcnt(0)
	v_mov_b32_e32 v29, v12
	v_mov_b32_e32 v12, v9
	v_pk_mul_f32 v[8:9], v[26:27], v[12:13] op_sel_hi:[0,1]
	v_pk_fma_f32 v[8:9], v[24:25], v[28:29], v[8:9] op_sel_hi:[0,1,1] neg_lo:[0,0,1] neg_hi:[0,0,1]
	v_pk_add_f32 v[12:13], v[10:11], v[8:9]
	v_add_u32_e32 v10, s30, v23
	v_add_u32_e32 v23, s30, v10
	v_and_b32_e32 v8, 0x3f0, v10
	v_and_b32_e32 v10, 0x3ec, v23
	v_add_u32_e32 v8, 0, v8
	v_add_u32_e32 v10, 0, v10
	ds_read2st64_b32 v[8:9], v8 offset1:4
	ds_read2st64_b32 v[10:11], v10 offset1:4
	s_waitcnt lgkmcnt(1)
	v_mov_b32_e32 v28, v8
	s_waitcnt lgkmcnt(0)
	v_mov_b32_e32 v29, v10
	v_mov_b32_e32 v10, v9
	v_pk_mul_f32 v[8:9], v[26:27], v[10:11] op_sel_hi:[0,1]
	v_pk_fma_f32 v[8:9], v[24:25], v[28:29], v[8:9] op_sel_hi:[0,1,1] neg_lo:[0,0,1] neg_hi:[0,0,1]
	v_pk_add_f32 v[10:11], v[16:17], v[8:9]
	v_add_u32_e32 v8, s30, v23
	v_and_b32_e32 v8, 0x3e8, v8
	v_add_u32_e32 v8, 0, v8
	ds_read2st64_b32 v[8:9], v8 offset1:4
	v_mov_b32_e32 v25, v26
	s_waitcnt lgkmcnt(0)
	v_mul_f32_e32 v16, v26, v9
	v_mul_lo_u32 v9, s30, v22
	v_and_b32_e32 v9, 0x3e4, v9
	v_add_u32_e32 v9, 0, v9
	ds_read2st64_b32 v[28:29], v9 offset1:4
	v_mul_f32_e32 v8, v24, v8
	s_waitcnt lgkmcnt(0)
	v_pk_mul_f32 v[24:25], v[24:25], v[28:29]
	s_nop 0
	v_mov_b32_e32 v9, v24
	v_mov_b32_e32 v17, v25
	v_pk_add_f32 v[8:9], v[8:9], v[16:17] neg_lo:[0,1] neg_hi:[0,1]
	s_nop 0
	v_pk_add_f32 v[8:9], v[18:19], v[8:9]
	s_cbranch_scc0 .LBB0_1354
	v_and_b32_e32 v5, 0xf8, v5
	v_lshl_or_b32 v6, v4, 8, v5
	v_add_u32_e32 v4, 0x8000, v6
	v_ashrrev_i32_e32 v5, 31, v4
	v_lshlrev_b64 v[4:5], 10, v[4:5]
	v_cvt_pk_bf16_f32 v7, v14, s0
	v_lshl_add_u64 v[4:5], v[2:3], 0, v[4:5]
	flat_store_short v[4:5], v7
	v_add_u32_e32 v4, 0x8001, v6
	v_ashrrev_i32_e32 v5, 31, v4
	v_lshlrev_b64 v[4:5], 10, v[4:5]
	v_cvt_pk_bf16_f32 v7, v15, s0
	v_lshl_add_u64 v[4:5], v[2:3], 0, v[4:5]
	flat_store_short v[4:5], v7
	v_add_u32_e32 v4, 0x8002, v6
	v_ashrrev_i32_e32 v5, 31, v4
	v_lshlrev_b64 v[4:5], 10, v[4:5]
	v_cvt_pk_bf16_f32 v7, v12, s0
	v_lshl_add_u64 v[4:5], v[2:3], 0, v[4:5]
	flat_store_short v[4:5], v7
	v_add_u32_e32 v4, 0x8003, v6
	v_ashrrev_i32_e32 v5, 31, v4
	v_lshlrev_b64 v[4:5], 10, v[4:5]
	v_cvt_pk_bf16_f32 v7, v13, s0
	v_lshl_add_u64 v[4:5], v[2:3], 0, v[4:5]
	flat_store_short v[4:5], v7
	v_add_u32_e32 v4, 0x8004, v6
	v_ashrrev_i32_e32 v5, 31, v4
	v_lshlrev_b64 v[4:5], 10, v[4:5]
	v_cvt_pk_bf16_f32 v7, v10, s0
	v_lshl_add_u64 v[4:5], v[2:3], 0, v[4:5]
	flat_store_short v[4:5], v7
	v_add_u32_e32 v4, 0x8005, v6
	v_ashrrev_i32_e32 v5, 31, v4
	v_lshlrev_b64 v[4:5], 10, v[4:5]
	v_cvt_pk_bf16_f32 v7, v11, s0
	v_lshl_add_u64 v[4:5], v[2:3], 0, v[4:5]
	flat_store_short v[4:5], v7
	v_add_u32_e32 v4, 0x8006, v6
	v_ashrrev_i32_e32 v5, 31, v4
	v_lshlrev_b64 v[4:5], 10, v[4:5]
	v_cvt_pk_bf16_f32 v7, v8, s0
	v_lshl_add_u64 v[4:5], v[2:3], 0, v[4:5]
	flat_store_short v[4:5], v7
	v_add_u32_e32 v4, 0x8007, v6
	v_ashrrev_i32_e32 v5, 31, v4
	v_add_u32_e32 v20, s65, v20
	s_mov_b32 s30, 0xffff
	v_lshlrev_b64 v[4:5], 10, v[4:5]
	v_cmp_lt_i32_e32 vcc, s30, v20
	v_cvt_pk_bf16_f32 v7, v9, s0
	v_lshl_add_u64 v[4:5], v[2:3], 0, v[4:5]
	s_or_b64 s[2:3], vcc, s[2:3]
	flat_store_short v[4:5], v7
	s_andn2_b64 exec, exec, s[2:3]
	s_cbranch_execnz .LBB0_1353

.LBB0_1480:
	s_lshl_b32 s0, s2, 2
	s_or_b32 s0, s0, s73
	s_ashr_i32 s1, s0, 31
	s_lshl_b32 s65, s2, 6
	s_lshl_b64 s[2:3], s[0:1], 14
	v_lshl_add_u64 v[36:37], v[112:113], 0, s[2:3]
	v_lshl_add_u64 v[40:41], v[108:109], 0, s[2:3]
	s_lshl_b64 s[2:3], s[0:1], 15
	s_add_u32 s2, s30, s2
	s_addc_u32 s3, s40, s3
	v_add_u32_e32 v16, s65, v145
	v_add_u32_e32 v28, s65, v147
	v_lshl_add_u64 v[44:45], v[106:107], 1, s[2:3]
	v_ashrrev_i32_e32 v17, 31, v16
	v_ashrrev_i32_e32 v29, 31, v28
	v_lshl_add_u64 v[44:45], v[44:45], 0, v[176:177]
	v_lshlrev_b64 v[20:21], 10, v[16:17]
	v_lshlrev_b64 v[32:33], 10, v[28:29]
	v_add_co_u32_e32 v48, vcc, 0x2000, v44
	v_lshl_add_u64 v[16:17], v[98:99], 0, v[20:21]
	v_lshl_add_u64 v[20:21], v[100:101], 0, v[20:21]
	v_lshl_add_u64 v[24:25], v[102:103], 1, v[36:37]
	v_lshl_add_u64 v[28:29], v[98:99], 0, v[32:33]
	v_lshl_add_u64 v[32:33], v[100:101], 0, v[32:33]
	v_lshl_add_u64 v[36:37], v[104:105], 1, v[36:37]
	v_addc_co_u32_e32 v49, vcc, 0, v45, vcc
	global_load_dwordx4 v[16:19], v[16:17], off
	s_nop 0
	global_load_dwordx4 v[20:23], v[20:21], off
	s_nop 0
	global_load_dwordx4 v[24:27], v[24:25], off
	s_nop 0
	global_load_dwordx4 v[28:31], v[28:29], off
	s_nop 0
	global_load_dwordx4 v[32:35], v[32:33], off
	s_nop 0
	global_load_dwordx4 v[36:39], v[36:37], off
	s_nop 0
	global_load_dwordx4 v[40:43], v[40:41], off
	s_nop 0
	global_load_dwordx4 v[44:47], v[44:45], off
	s_nop 0
	global_load_dwordx4 v[48:51], v[48:49], off
	s_and_saveexec_b64 s[2:3], s[60:61]
	s_cbranch_execz .LBB0_1482
	s_lshl_b64 s[0:1], s[0:1], 9
	v_lshl_add_u64 v[52:53], v[114:115], 0, s[0:1]
	global_load_dword v149, v[52:53], off

.LBB0_1494:
	s_or_b64 exec, exec, s[2:3]
	v_cvt_pk_bf16_f32 v62, v64, v65
	v_cvt_pk_bf16_f32 v63, v60, v61
	ds_write_b64 v137, v[62:63]
	v_cvt_pk_bf16_f32 v60, v76, v77
	v_cvt_pk_bf16_f32 v61, v78, v79
	v_cvt_pk_bf16_f32 v62, v80, v81
	v_cvt_pk_bf16_f32 v63, v82, v83
	ds_write2_b64 v134, v[60:61], v[62:63] offset1:4
	v_cvt_pk_bf16_f32 v60, v84, v85
	v_cvt_pk_bf16_f32 v61, v86, v87
	v_cvt_pk_bf16_f32 v62, v88, v89
	v_cvt_pk_bf16_f32 v63, v90, v91
	ds_write2_b64 v134, v[60:61], v[62:63] offset0:8 offset1:12
	v_add_u32_e32 v60, v163, v160
	s_waitcnt lgkmcnt(0)
	s_barrier
	ds_read_b128 v[62:65], v60
	ds_read_b128 v[76:79], v132
	ds_read_b128 v[80:83], v133
	ds_read_b128 v[84:87], v60 offset:64
	s_waitcnt lgkmcnt(0)
	v_mfma_f32_16x16x32_bf16 v[76:79], v[62:65], v[76:79], 0
	v_add_u32_e32 v61, s64, v125
	s_and_b64 s[2:3], s[0:1], exec
	s_mov_b32 s2, 0x23100
	v_mfma_f32_16x16x32_bf16 v[62:65], v[62:65], v[80:83], 0
	ds_read_b128 v[80:83], v130
	ds_read_b128 v[88:91], v131
	s_cselect_b32 s2, s2, 0x8800
	s_waitcnt lgkmcnt(0)
	v_mfma_f32_16x16x32_bf16 v[76:79], v[84:87], v[80:83], v[76:79]
	ds_read_b128 v[80:83], v60 offset:128
	v_mfma_f32_16x16x32_bf16 v[62:65], v[84:87], v[88:91], v[62:65]
	ds_read_b128 v[84:87], v128
	ds_read_b128 v[88:91], v129
	s_waitcnt lgkmcnt(0)
	v_mfma_f32_16x16x32_bf16 v[76:79], v[80:83], v[84:87], v[76:79]
	ds_read_b128 v[84:87], v60 offset:192
	v_mfma_f32_16x16x32_bf16 v[62:65], v[80:83], v[88:91], v[62:65]
	ds_read_b128 v[80:83], v126
	ds_read_b128 v[88:91], v127
	s_waitcnt lgkmcnt(0)
	v_mfma_f32_16x16x32_bf16 v[76:79], v[84:87], v[80:83], v[76:79]
	ds_read_b128 v[80:83], v61
	s_waitcnt lgkmcnt(0)
	v_sub_f32_e32 v61, v194, v80
	v_mul_f32_e32 v61, 0x3fb8aa3b, v61
	v_exp_f32_e32 v80, v61
	v_sub_f32_e32 v61, v194, v81
	v_mul_f32_e32 v61, 0x3fb8aa3b, v61
	v_exp_f32_e32 v81, v61
	v_sub_f32_e32 v61, v194, v82
	v_mul_f32_e32 v61, 0x3fb8aa3b, v61
	v_exp_f32_e32 v82, v61
	v_sub_f32_e32 v61, v194, v83
	v_mul_f32_e32 v61, 0x3fb8aa3b, v61
	v_mfma_f32_16x16x32_bf16 v[64:67], v[84:87], v[88:91], v[62:65]
	v_exp_f32_e32 v83, v61
	v_sub_f32_e32 v73, v73, v77
	v_sub_f32_e32 v72, v72, v76
	v_sub_f32_e32 v63, v75, v79
	v_sub_f32_e32 v62, v74, v78
	v_pk_mul_f32 v[74:75], v[72:73], v[80:81]
	v_pk_mul_f32 v[76:77], v[62:63], v[82:83]
	v_cvt_pk_bf16_f32 v72, v72, v73
	v_cvt_pk_bf16_f32 v73, v62, v63
	v_add_u32_e32 v62, v170, v164
	v_sub_f32_e32 v67, v71, v67
	v_sub_f32_e32 v66, v70, v66
	v_sub_f32_e32 v65, v69, v65
	v_sub_f32_e32 v64, v68, v64
	ds_write_b64 v62, v[72:73]
	v_cvt_pk_bf16_f32 v72, v74, v75
	v_cvt_pk_bf16_f32 v73, v76, v77
	v_pk_mul_f32 v[68:69], v[64:65], v[80:81]
	v_pk_mul_f32 v[70:71], v[66:67], v[82:83]
	v_cvt_pk_bf16_f32 v64, v64, v65
	v_cvt_pk_bf16_f32 v65, v66, v67
	v_add_u32_e32 v63, v171, v164
	ds_write_b64 v124, v[72:73]
	ds_write_b64 v63, v[64:65]
	v_cvt_pk_bf16_f32 v64, v68, v69
	v_cvt_pk_bf16_f32 v65, v70, v71
	ds_write_b64 v123, v[64:65]
	v_add_u32_e32 v64, v170, v160
	s_waitcnt lgkmcnt(0)
	s_barrier
	ds_read_b128 v[66:69], v64
	v_add_u32_e32 v61, v162, v160
	v_add_u32_e32 v65, v171, v160
	v_mul_f32_e32 v86, 0x3fb8aa3b, v194
	ds_read_b128 v[70:73], v61
	ds_read_b128 v[74:77], v65
	ds_read_b128 v[78:81], v193
	ds_read_b128 v[82:85], v193 offset:2304
	v_exp_f32_e32 v90, v86
	ds_read_b128 v[86:89], v120
	s_waitcnt lgkmcnt(0)
	v_mfma_f32_16x16x32_bf16 v[66:69], v[66:69], v[70:73], 0
	v_mul_f32_e64 v2, v2, v90
	v_mul_f32_e64 v3, v3, v90
	v_pk_mul_f32 v[0:1], v[0:1], v[90:91] op_sel_hi:[1,0]
	v_pk_mul_f32 v[10:11], v[10:11], v[90:91] op_sel_hi:[1,0]
	v_mfma_f32_16x16x32_bf16 v[70:73], v[74:77], v[70:73], 0
	ds_read_b128 v[74:77], v193 offset:4608
	v_pk_mul_f32 v[8:9], v[8:9], v[90:91] op_sel_hi:[1,0]
	v_pk_mul_f32 v[6:7], v[6:7], v[90:91] op_sel_hi:[1,0]
	v_mfma_f32_16x16x32_bf16 v[0:3], v[78:81], v[86:89], v[0:3]
	ds_read_b128 v[78:81], v193 offset:6912
	v_pk_mul_f32 v[4:5], v[4:5], v[90:91] op_sel_hi:[1,0]
	v_pk_mul_f32 v[14:15], v[14:15], v[90:91] op_sel_hi:[1,0]
	v_pk_mul_f32 v[12:13], v[12:13], v[90:91] op_sel_hi:[1,0]
	v_mfma_f32_16x16x32_bf16 v[8:11], v[82:85], v[86:89], v[8:11]
	ds_read_b128 v[82:85], v122
	s_waitcnt lgkmcnt(0)
	v_mfma_f32_16x16x32_bf16 v[4:7], v[74:77], v[86:89], v[4:7]
	ds_read_b128 v[74:77], v61 offset:64
	v_mfma_f32_16x16x32_bf16 v[12:15], v[78:81], v[86:89], v[12:15]
	ds_read_b128 v[78:81], v121
	s_waitcnt lgkmcnt(0)
	v_mfma_f32_16x16x32_bf16 v[66:69], v[82:85], v[74:77], v[66:69]
	ds_read_b128 v[82:85], v193 offset:64
	ds_read_b128 v[86:89], v120 offset:64
	v_mfma_f32_16x16x32_bf16 v[70:73], v[78:81], v[74:77], v[70:73]
	ds_read_b128 v[74:77], v193 offset:2368
	ds_read_b128 v[78:81], v193 offset:4672
	s_waitcnt lgkmcnt(0)
	v_mfma_f32_16x16x32_bf16 v[8:11], v[74:77], v[86:89], v[8:11]
	ds_read_b128 v[74:77], v193 offset:6976
	v_mfma_f32_16x16x32_bf16 v[4:7], v[78:81], v[86:89], v[4:7]
	ds_read_b32 v78, v195
	s_waitcnt lgkmcnt(0)
	v_mfma_f32_16x16x32_bf16 v[12:15], v[74:77], v[86:89], v[12:15]
	v_mul_f32_e32 v74, 0x3fb8aa3b, v78
	v_exp_f32_e32 v74, v74
	v_lshl_add_u32 v76, s63, 6, v93
	v_mfma_f32_16x16x32_bf16 v[0:3], v[82:85], v[86:89], v[0:3]
	v_ashrrev_i32_e32 v77, 31, v76
	v_lshlrev_b64 v[76:77], 10, v[76:77]
	v_pk_fma_f32 v[54:55], v[54:55], v[74:75], v[68:69] op_sel_hi:[1,0,1]
	v_pk_fma_f32 v[52:53], v[52:53], v[74:75], v[66:67] op_sel_hi:[1,0,1]
	v_pk_fma_f32 v[56:57], v[56:57], v[74:75], v[70:71] op_sel_hi:[1,0,1]
	v_cvt_pk_bf16_f32 v52, v52, v53
	v_cvt_pk_bf16_f32 v53, v54, v55
	v_lshl_add_u64 v[54:55], v[116:117], 0, v[76:77]
	s_waitcnt vmcnt(0)
	global_store_dwordx2 v[54:55], v[52:53], off
	v_pk_fma_f32 v[52:53], v[58:59], v[74:75], v[72:73] op_sel_hi:[1,0,1]
	v_cvt_pk_bf16_f32 v56, v56, v57
	v_cvt_pk_bf16_f32 v57, v52, v53
	v_cvt_pk_bf16_f32 v52, v0, v1
	v_cvt_pk_bf16_f32 v53, v2, v3
	global_store_dwordx2 v[54:55], v[56:57], off offset:32
	ds_write_b64 v119, v[52:53]
	v_cvt_pk_bf16_f32 v52, v8, v9
	v_cvt_pk_bf16_f32 v53, v10, v11
	ds_write_b64 v118, v[52:53]
	v_cvt_pk_bf16_f32 v52, v4, v5
	v_cvt_pk_bf16_f32 v53, v6, v7
	ds_write_b64 v111, v[52:53]
	v_cvt_pk_bf16_f32 v52, v12, v13
	v_cvt_pk_bf16_f32 v53, v14, v15
	ds_write_b64 v97, v[52:53]
	v_add_u32_e32 v52, s2, v165
	ds_write_b128 v150, v[16:19]
	ds_write_b128 v151, v[20:23] offset:17408
	v_add_u32_e32 v16, v52, v152
	ds_write_b128 v16, v[24:27]
	ds_write_b128 v153, v[28:31]
	ds_write_b128 v154, v[32:35] offset:17408
	v_add_u32_e32 v16, v52, v155
	ds_write_b128 v16, v[36:39]
	ds_write_b128 v156, v[40:43] offset:53248
	ds_write_b128 v156, v[44:47] offset:62464
	ds_write_b128 v157, v[48:51]
	s_and_saveexec_b64 s[2:3], s[60:61]
	s_cbranch_execz .LBB0_1471
	s_and_b64 s[0:1], s[0:1], exec
	s_cselect_b32 s0, 0x27900, s89
	v_add_u32_e32 v16, s0, v158
	ds_write_b32 v16, v149
	s_branch .LBB0_1471
